# XCD-local grid barrier: one monotonic per-XCD arrival counter that every workgroup polls (no atomic-with-return, no separate generation word)
# baseline (speedup 1.0000x reference)
.LBB0_498:
	s_waitcnt vmcnt(0)
	s_barrier
	s_and_saveexec_b64 s[4:5], s[10:11]
	s_cbranch_execz .LBB0_550
	s_add_i32 s6, 0, 0x20160
	v_mov_b32_e32 v0, s6
	s_waitcnt vmcnt(0) expcnt(0) lgkmcnt(0)
	s_cmp_eq_u32 s98, 0
	s_cbranch_scc1 .Leinv_1
	buffer_inv sc1
	s_and_b32 s99, s2, 7
	s_lshl_b32 s99, s99, 8
	s_add_u32 s99, s99, 0xd000
	v_mov_b32_e32 v0, s99
	v_mov_b32_e32 v1, 1
	global_atomic_add v0, v1, s[52:53]
.Lfb_poll_1:
	global_load_dword v2, v0, s[52:53] sc1
	s_waitcnt vmcnt(0)
	v_readfirstlane_b32 s99, v2
	s_cmpk_lt_u32 s99, 0x20
	s_cbranch_scc0 .Lfb_done_1
	s_sleep 1
	s_branch .Lfb_poll_1
.Lfb_done_1:
	s_branch .LBB0_550
.Leinv_1:
	ds_read_b32 v2, v0
	s_add_i32 s6, 0, 0x20164
	v_mov_b32_e32 v0, s6
	ds_read_b32 v0, v0
	s_waitcnt lgkmcnt(1)
	v_cmp_ne_u32_e32 vcc, 0, v2
	s_cbranch_vccnz .LBB0_514
	s_load_dwordx2 s[12:13], s[0:1], 0xa8
	s_load_dword s9, s[0:1], 0xb0
	s_add_u32 s6, s34, 0x4200
	s_addc_u32 s7, s35, 0
	s_add_u32 s8, s34, 0x4400
	s_waitcnt lgkmcnt(0)
	s_mul_i32 s54, s13, s12
	s_mul_i32 s54, s54, s9
	s_addc_u32 s9, s35, 0
	s_add_u32 s12, s34, 0x4500
	s_addc_u32 s13, s35, 0
	s_add_u32 s14, s34, 0x4600
	s_addc_u32 s15, s35, 0
	s_add_u32 s16, s34, 0x4700
	s_addc_u32 s17, s35, 0
	s_add_u32 s18, s34, 0x4800
	s_addc_u32 s19, s35, 0
	s_add_u32 s20, s34, 0x4900
	s_addc_u32 s21, s35, 0
	s_add_u32 s22, s34, 0x4a00
	s_addc_u32 s23, s35, 0
	s_add_u32 s24, s34, 0x4b00
	s_addc_u32 s25, s35, 0
	s_add_u32 s26, s34, 0x4c00
	s_addc_u32 s27, s35, 0
	s_add_u32 s28, s34, 0x4d00
	s_addc_u32 s29, s35, 0
	s_add_u32 s30, s34, 0x4e00
	s_addc_u32 s31, s35, 0
	s_add_u32 s36, s34, 0x4f00
	s_addc_u32 s37, s35, 0
	s_add_u32 s38, s34, 0x5000
	s_addc_u32 s39, s35, 0
	s_add_u32 s40, s34, 0x5100
	s_addc_u32 s41, s35, 0
	s_add_u32 s42, s34, 0x5200
	s_addc_u32 s43, s35, 0
	s_add_u32 s44, s34, 0x5300
	s_addc_u32 s45, s35, 0
	s_mov_b32 s55, 1
	v_mov_b32_e32 v16, 0
	s_branch .LBB0_502

.LBB0_558:
	s_barrier
	s_waitcnt vmcnt(0)
	s_barrier
	s_and_saveexec_b64 s[4:5], s[10:11]
	s_cbranch_execz .LBB0_610
	s_add_i32 s6, 0, 0x20160
	s_waitcnt vmcnt(12)
	v_mov_b32_e32 v0, s6
	s_waitcnt vmcnt(0) expcnt(0) lgkmcnt(0)
	s_cmp_eq_u32 s98, 0
	s_cbranch_scc1 .Leinv_2
	buffer_inv sc1
	s_and_b32 s99, s2, 7
	s_lshl_b32 s99, s99, 8
	s_add_u32 s99, s99, 0xd000
	v_mov_b32_e32 v0, s99
	v_mov_b32_e32 v1, 1
	global_atomic_add v0, v1, s[52:53]
.Lfb_poll_2:
	global_load_dword v2, v0, s[52:53] sc1
	s_waitcnt vmcnt(0)
	v_readfirstlane_b32 s99, v2
	s_cmpk_lt_u32 s99, 0x40
	s_cbranch_scc0 .Lfb_done_2
	s_sleep 1
	s_branch .Lfb_poll_2
.Lfb_done_2:
	s_branch .LBB0_610
.Leinv_2:
	ds_read_b32 v2, v0
	s_add_i32 s6, 0, 0x20164
	v_mov_b32_e32 v0, s6
	ds_read_b32 v0, v0
	s_waitcnt lgkmcnt(1)
	v_cmp_ne_u32_e32 vcc, 0, v2
	s_cbranch_vccnz .LBB0_574
	s_load_dwordx2 s[12:13], s[0:1], 0xa8
	s_load_dword s9, s[0:1], 0xb0
	s_add_u32 s6, s34, 0x4200
	s_addc_u32 s7, s35, 0
	s_add_u32 s8, s34, 0x4400
	s_waitcnt lgkmcnt(0)
	s_mul_i32 s54, s13, s12
	s_mul_i32 s54, s54, s9
	s_addc_u32 s9, s35, 0
	s_add_u32 s12, s34, 0x4500
	s_addc_u32 s13, s35, 0
	s_add_u32 s14, s34, 0x4600
	s_addc_u32 s15, s35, 0
	s_add_u32 s16, s34, 0x4700
	s_addc_u32 s17, s35, 0
	s_add_u32 s18, s34, 0x4800
	s_addc_u32 s19, s35, 0
	s_add_u32 s20, s34, 0x4900
	s_addc_u32 s21, s35, 0
	s_add_u32 s22, s34, 0x4a00
	s_addc_u32 s23, s35, 0
	s_add_u32 s24, s34, 0x4b00
	s_addc_u32 s25, s35, 0
	s_add_u32 s26, s34, 0x4c00
	s_addc_u32 s27, s35, 0
	s_add_u32 s28, s34, 0x4d00
	s_addc_u32 s29, s35, 0
	s_add_u32 s30, s34, 0x4e00
	s_addc_u32 s31, s35, 0
	s_add_u32 s36, s34, 0x4f00
	s_addc_u32 s37, s35, 0
	s_add_u32 s38, s34, 0x5000
	s_addc_u32 s39, s35, 0
	s_add_u32 s40, s34, 0x5100
	s_addc_u32 s41, s35, 0
	s_add_u32 s42, s34, 0x5200
	s_addc_u32 s43, s35, 0
	s_add_u32 s44, s34, 0x5300
	s_addc_u32 s45, s35, 0
	s_mov_b32 s55, 1
	v_mov_b32_e32 v16, 0
	s_branch .LBB0_562

.LBB0_621:
	s_waitcnt vmcnt(0)
	s_barrier
	s_and_saveexec_b64 s[4:5], s[10:11]
	s_cbranch_execz .LBB0_673
	s_add_i32 s6, 0, 0x20160
	s_waitcnt vmcnt(23)
	v_mov_b32_e32 v0, s6
	s_waitcnt vmcnt(0) expcnt(0) lgkmcnt(0)
	s_cmp_eq_u32 s98, 0
	s_cbranch_scc1 .Leinv_3
	buffer_inv sc1
	s_and_b32 s99, s2, 7
	s_lshl_b32 s99, s99, 8
	s_add_u32 s99, s99, 0xd000
	v_mov_b32_e32 v0, s99
	v_mov_b32_e32 v1, 1
	global_atomic_add v0, v1, s[52:53]
.Lfb_poll_3:
	global_load_dword v2, v0, s[52:53] sc1
	s_waitcnt vmcnt(0)
	v_readfirstlane_b32 s99, v2
	s_cmpk_lt_u32 s99, 0x60
	s_cbranch_scc0 .Lfb_done_3
	s_sleep 1
	s_branch .Lfb_poll_3
.Lfb_done_3:
	s_branch .LBB0_673
.Leinv_3:
	ds_read_b32 v2, v0
	s_add_i32 s6, 0, 0x20164
	v_mov_b32_e32 v0, s6
	ds_read_b32 v0, v0
	s_waitcnt lgkmcnt(1)
	v_cmp_ne_u32_e32 vcc, 0, v2
	s_cbranch_vccnz .LBB0_637
	s_load_dwordx2 s[12:13], s[0:1], 0xa8
	s_load_dword s9, s[0:1], 0xb0
	s_add_u32 s6, s34, 0x4200
	s_addc_u32 s7, s35, 0
	s_add_u32 s8, s34, 0x4400
	s_waitcnt lgkmcnt(0)
	s_mul_i32 s54, s13, s12
	s_mul_i32 s54, s54, s9
	s_addc_u32 s9, s35, 0
	s_add_u32 s12, s34, 0x4500
	s_addc_u32 s13, s35, 0
	s_add_u32 s14, s34, 0x4600
	s_addc_u32 s15, s35, 0
	s_add_u32 s16, s34, 0x4700
	s_addc_u32 s17, s35, 0
	s_add_u32 s18, s34, 0x4800
	s_addc_u32 s19, s35, 0
	s_add_u32 s20, s34, 0x4900
	s_addc_u32 s21, s35, 0
	s_add_u32 s22, s34, 0x4a00
	s_addc_u32 s23, s35, 0
	s_add_u32 s24, s34, 0x4b00
	s_addc_u32 s25, s35, 0
	s_add_u32 s26, s34, 0x4c00
	s_addc_u32 s27, s35, 0
	s_add_u32 s28, s34, 0x4d00
	s_addc_u32 s29, s35, 0
	s_add_u32 s30, s34, 0x4e00
	s_addc_u32 s31, s35, 0
	s_add_u32 s36, s34, 0x4f00
	s_addc_u32 s37, s35, 0
	s_add_u32 s38, s34, 0x5000
	s_addc_u32 s39, s35, 0
	s_add_u32 s40, s34, 0x5100
	s_addc_u32 s41, s35, 0
	s_add_u32 s42, s34, 0x5200
	s_addc_u32 s43, s35, 0
	s_add_u32 s44, s34, 0x5300
	s_addc_u32 s45, s35, 0
	s_mov_b32 s55, 1
	v_mov_b32_e32 v16, 0
	s_branch .LBB0_625

.LBB0_723:
	s_waitcnt vmcnt(0)
	s_waitcnt lgkmcnt(0)
	s_barrier
	s_and_saveexec_b64 s[4:5], s[10:11]
	s_cbranch_execz .LBB0_775
	s_add_i32 s6, 0, 0x20160
	v_mov_b32_e32 v0, s6
	s_waitcnt vmcnt(0) expcnt(0) lgkmcnt(0)
	s_cmp_eq_u32 s98, 0
	s_cbranch_scc1 .Leinv_4
	buffer_inv sc1
	s_and_b32 s99, s2, 7
	s_lshl_b32 s99, s99, 8
	s_add_u32 s99, s99, 0xd000
	v_mov_b32_e32 v0, s99
	v_mov_b32_e32 v1, 1
	global_atomic_add v0, v1, s[52:53]
.Lfb_poll_4:
	global_load_dword v2, v0, s[52:53] sc1
	s_waitcnt vmcnt(0)
	v_readfirstlane_b32 s99, v2
	s_cmpk_lt_u32 s99, 0x80
	s_cbranch_scc0 .Lfb_done_4
	s_sleep 1
	s_branch .Lfb_poll_4
.Lfb_done_4:
	s_branch .LBB0_775
.Leinv_4:
	ds_read_b32 v2, v0
	s_add_i32 s6, 0, 0x20164
	v_mov_b32_e32 v0, s6
	ds_read_b32 v0, v0
	s_waitcnt lgkmcnt(1)
	v_cmp_ne_u32_e32 vcc, 0, v2
	s_cbranch_vccnz .LBB0_739
	s_load_dwordx2 s[12:13], s[0:1], 0xa8
	s_load_dword s9, s[0:1], 0xb0
	s_add_u32 s6, s34, 0x4200
	s_addc_u32 s7, s35, 0
	s_add_u32 s8, s34, 0x4400
	s_waitcnt lgkmcnt(0)
	s_mul_i32 s54, s13, s12
	s_mul_i32 s54, s54, s9
	s_addc_u32 s9, s35, 0
	s_add_u32 s12, s34, 0x4500
	s_addc_u32 s13, s35, 0
	s_add_u32 s14, s34, 0x4600
	s_addc_u32 s15, s35, 0
	s_add_u32 s16, s34, 0x4700
	s_addc_u32 s17, s35, 0
	s_add_u32 s18, s34, 0x4800
	s_addc_u32 s19, s35, 0
	s_add_u32 s20, s34, 0x4900
	s_addc_u32 s21, s35, 0
	s_add_u32 s22, s34, 0x4a00
	s_addc_u32 s23, s35, 0
	s_add_u32 s24, s34, 0x4b00
	s_addc_u32 s25, s35, 0
	s_add_u32 s26, s34, 0x4c00
	s_addc_u32 s27, s35, 0
	s_add_u32 s28, s34, 0x4d00
	s_addc_u32 s29, s35, 0
	s_add_u32 s30, s34, 0x4e00
	s_addc_u32 s31, s35, 0
	s_add_u32 s36, s34, 0x4f00
	s_addc_u32 s37, s35, 0
	s_add_u32 s38, s34, 0x5000
	s_addc_u32 s39, s35, 0
	s_add_u32 s40, s34, 0x5100
	s_addc_u32 s41, s35, 0
	s_add_u32 s42, s34, 0x5200
	s_addc_u32 s43, s35, 0
	s_add_u32 s44, s34, 0x5300
	s_addc_u32 s45, s35, 0
	s_mov_b32 s55, 1
	v_mov_b32_e32 v16, 0
	s_branch .LBB0_727

.Lfb_poll_5:
	global_load_dword v2, v0, s[52:53] sc1
	s_waitcnt vmcnt(0)
	v_readfirstlane_b32 s99, v2
	s_cmpk_lt_u32 s99, 0xa0
	s_cbranch_scc0 .Lfb_done_5
	s_sleep 1
	s_branch .Lfb_poll_5
.Lfb_done_5:
	s_branch .LBB0_843
.Leinv_5:
	ds_read_b32 v2, v0
	s_add_i32 s6, 0, 0x20164
	v_mov_b32_e32 v0, s6
	ds_read_b32 v0, v0
	s_waitcnt lgkmcnt(1)
	v_cmp_ne_u32_e32 vcc, 0, v2
	s_cbranch_vccnz .LBB0_807
	s_load_dwordx2 s[12:13], s[0:1], 0xa8
	s_load_dword s9, s[0:1], 0xb0
	s_add_u32 s6, s34, 0x4200
	s_addc_u32 s7, s35, 0
	s_add_u32 s8, s34, 0x4400
	s_waitcnt lgkmcnt(0)
	s_mul_i32 s54, s13, s12
	s_mul_i32 s54, s54, s9
	s_addc_u32 s9, s35, 0
	s_add_u32 s12, s34, 0x4500
	s_addc_u32 s13, s35, 0
	s_add_u32 s14, s34, 0x4600
	s_addc_u32 s15, s35, 0
	s_add_u32 s16, s34, 0x4700
	s_addc_u32 s17, s35, 0
	s_add_u32 s18, s34, 0x4800
	s_addc_u32 s19, s35, 0
	s_add_u32 s20, s34, 0x4900
	s_addc_u32 s21, s35, 0
	s_add_u32 s22, s34, 0x4a00
	s_addc_u32 s23, s35, 0
	s_add_u32 s24, s34, 0x4b00
	s_addc_u32 s25, s35, 0
	s_add_u32 s26, s34, 0x4c00
	s_addc_u32 s27, s35, 0
	s_add_u32 s28, s34, 0x4d00
	s_addc_u32 s29, s35, 0
	s_add_u32 s30, s34, 0x4e00
	s_addc_u32 s31, s35, 0
	s_add_u32 s36, s34, 0x4f00
	s_addc_u32 s37, s35, 0
	s_add_u32 s38, s34, 0x5000
	s_addc_u32 s39, s35, 0
	s_add_u32 s40, s34, 0x5100
	s_addc_u32 s41, s35, 0
	s_add_u32 s42, s34, 0x5200
	s_addc_u32 s43, s35, 0
	s_add_u32 s44, s34, 0x5300
	s_addc_u32 s45, s35, 0
	s_mov_b32 s55, 1
	v_mov_b32_e32 v16, 0
	s_branch .LBB0_795

.Lfb_poll_6:
	global_load_dword v2, v0, s[52:53] sc1
	s_waitcnt vmcnt(0)
	v_readfirstlane_b32 s99, v2
	s_cmpk_lt_u32 s99, 0xc0
	s_cbranch_scc0 .Lfb_done_6
	s_sleep 1
	s_branch .Lfb_poll_6
.Lfb_done_6:
	s_branch .LBB0_941
.Leinv_6:
	ds_read_b32 v2, v0
	s_add_i32 s6, 0, 0x20164
	v_mov_b32_e32 v0, s6
	ds_read_b32 v0, v0
	s_waitcnt lgkmcnt(1)
	v_cmp_ne_u32_e32 vcc, 0, v2
	s_cbranch_vccnz .LBB0_905
	s_load_dwordx2 s[12:13], s[0:1], 0xa8
	s_load_dword s9, s[0:1], 0xb0
	s_add_u32 s6, s34, 0x4200
	s_addc_u32 s7, s35, 0
	s_add_u32 s8, s34, 0x4400
	s_waitcnt lgkmcnt(0)
	s_mul_i32 s54, s13, s12
	s_mul_i32 s54, s54, s9
	s_addc_u32 s9, s35, 0
	s_add_u32 s12, s34, 0x4500
	s_addc_u32 s13, s35, 0
	s_add_u32 s14, s34, 0x4600
	s_addc_u32 s15, s35, 0
	s_add_u32 s16, s34, 0x4700
	s_addc_u32 s17, s35, 0
	s_add_u32 s18, s34, 0x4800
	s_addc_u32 s19, s35, 0
	s_add_u32 s20, s34, 0x4900
	s_addc_u32 s21, s35, 0
	s_add_u32 s22, s34, 0x4a00
	s_addc_u32 s23, s35, 0
	s_add_u32 s24, s34, 0x4b00
	s_addc_u32 s25, s35, 0
	s_add_u32 s26, s34, 0x4c00
	s_addc_u32 s27, s35, 0
	s_add_u32 s28, s34, 0x4d00
	s_addc_u32 s29, s35, 0
	s_add_u32 s30, s34, 0x4e00
	s_addc_u32 s31, s35, 0
	s_add_u32 s36, s34, 0x4f00
	s_addc_u32 s37, s35, 0
	s_add_u32 s38, s34, 0x5000
	s_addc_u32 s39, s35, 0
	s_add_u32 s40, s34, 0x5100
	s_addc_u32 s41, s35, 0
	s_add_u32 s42, s34, 0x5200
	s_addc_u32 s43, s35, 0
	s_add_u32 s44, s34, 0x5300
	s_addc_u32 s45, s35, 0
	s_mov_b32 s55, 1
	v_mov_b32_e32 v16, 0
	s_branch .LBB0_893

.Lfb_poll_7:
	global_load_dword v2, v0, s[52:53] sc1
	s_waitcnt vmcnt(0)
	v_readfirstlane_b32 s99, v2
	s_cmpk_lt_u32 s99, 0xe0
	s_cbranch_scc0 .Lfb_done_7
	s_sleep 1
	s_branch .Lfb_poll_7
.Lfb_done_7:
	s_branch .LBB0_1051
.Leinv_7:
	ds_read_b32 v2, v0
	s_add_i32 s6, 0, 0x20164
	v_mov_b32_e32 v0, s6
	ds_read_b32 v0, v0
	s_waitcnt lgkmcnt(1)
	v_cmp_ne_u32_e32 vcc, 0, v2
	s_cbranch_vccnz .LBB0_1015
	s_load_dwordx2 s[12:13], s[0:1], 0xa8
	s_load_dword s9, s[0:1], 0xb0
	s_add_u32 s6, s34, 0x4200
	s_addc_u32 s7, s35, 0
	s_add_u32 s8, s34, 0x4400
	s_waitcnt lgkmcnt(0)
	s_mul_i32 s54, s13, s12
	s_mul_i32 s54, s54, s9
	s_addc_u32 s9, s35, 0
	s_add_u32 s12, s34, 0x4500
	s_addc_u32 s13, s35, 0
	s_add_u32 s14, s34, 0x4600
	s_addc_u32 s15, s35, 0
	s_add_u32 s16, s34, 0x4700
	s_addc_u32 s17, s35, 0
	s_add_u32 s18, s34, 0x4800
	s_addc_u32 s19, s35, 0
	s_add_u32 s20, s34, 0x4900
	s_addc_u32 s21, s35, 0
	s_add_u32 s22, s34, 0x4a00
	s_addc_u32 s23, s35, 0
	s_add_u32 s24, s34, 0x4b00
	s_addc_u32 s25, s35, 0
	s_add_u32 s26, s34, 0x4c00
	s_addc_u32 s27, s35, 0
	s_add_u32 s28, s34, 0x4d00
	s_addc_u32 s29, s35, 0
	s_add_u32 s30, s34, 0x4e00
	s_addc_u32 s31, s35, 0
	s_add_u32 s36, s34, 0x4f00
	s_addc_u32 s37, s35, 0
	s_add_u32 s38, s34, 0x5000
	s_addc_u32 s39, s35, 0
	s_add_u32 s40, s34, 0x5100
	s_addc_u32 s41, s35, 0
	s_add_u32 s42, s34, 0x5200
	s_addc_u32 s43, s35, 0
	s_add_u32 s44, s34, 0x5300
	s_addc_u32 s45, s35, 0
	s_mov_b32 s55, 1
	v_mov_b32_e32 v16, 0
	s_branch .LBB0_1003

.Lfb_poll_8:
	global_load_dword v2, v0, s[52:53] sc1
	s_waitcnt vmcnt(0)
	v_readfirstlane_b32 s99, v2
	s_cmpk_lt_u32 s99, 0x100
	s_cbranch_scc0 .Lfb_done_8
	s_sleep 1
	s_branch .Lfb_poll_8
.Lfb_done_8:
	s_branch .LBB0_1127
.Leinv_8:
	ds_read_b32 v2, v0
	s_add_i32 s6, 0, 0x20164
	v_mov_b32_e32 v0, s6
	ds_read_b32 v0, v0
	s_waitcnt lgkmcnt(1)
	v_cmp_ne_u32_e32 vcc, 0, v2
	s_cbranch_vccnz .LBB0_1091
	s_load_dwordx2 s[12:13], s[0:1], 0xa8
	s_load_dword s9, s[0:1], 0xb0
	s_add_u32 s6, s34, 0x4200
	s_addc_u32 s7, s35, 0
	s_add_u32 s8, s34, 0x4400
	s_waitcnt lgkmcnt(0)
	s_mul_i32 s54, s13, s12
	s_mul_i32 s54, s54, s9
	s_addc_u32 s9, s35, 0
	s_add_u32 s12, s34, 0x4500
	s_addc_u32 s13, s35, 0
	s_add_u32 s14, s34, 0x4600
	s_addc_u32 s15, s35, 0
	s_add_u32 s16, s34, 0x4700
	s_addc_u32 s17, s35, 0
	s_add_u32 s18, s34, 0x4800
	s_addc_u32 s19, s35, 0
	s_add_u32 s20, s34, 0x4900
	s_addc_u32 s21, s35, 0
	s_add_u32 s22, s34, 0x4a00
	s_addc_u32 s23, s35, 0
	s_add_u32 s24, s34, 0x4b00
	s_addc_u32 s25, s35, 0
	s_add_u32 s26, s34, 0x4c00
	s_addc_u32 s27, s35, 0
	s_add_u32 s28, s34, 0x4d00
	s_addc_u32 s29, s35, 0
	s_add_u32 s30, s34, 0x4e00
	s_addc_u32 s31, s35, 0
	s_add_u32 s36, s34, 0x4f00
	s_addc_u32 s37, s35, 0
	s_add_u32 s38, s34, 0x5000
	s_addc_u32 s39, s35, 0
	s_add_u32 s40, s34, 0x5100
	s_addc_u32 s41, s35, 0
	s_add_u32 s42, s34, 0x5200
	s_addc_u32 s43, s35, 0
	s_add_u32 s44, s34, 0x5300
	s_addc_u32 s45, s35, 0
	s_mov_b32 s55, 1
	v_mov_b32_e32 v16, 0
	s_branch .LBB0_1079

.Lfb_poll_9:
	global_load_dword v2, v0, s[52:53] sc1
	s_waitcnt vmcnt(0)
	v_readfirstlane_b32 s99, v2
	s_cmpk_lt_u32 s99, 0x120
	s_cbranch_scc0 .Lfb_done_9
	s_sleep 1
	s_branch .Lfb_poll_9
.Lfb_done_9:
	s_branch .LBB0_1221
.Leinv_9:
	ds_read_b32 v2, v0
	s_add_i32 s6, 0, 0x20164
	v_mov_b32_e32 v0, s6
	ds_read_b32 v0, v0
	s_waitcnt lgkmcnt(1)
	v_cmp_ne_u32_e32 vcc, 0, v2
	s_cbranch_vccnz .LBB0_1185
	s_load_dwordx2 s[12:13], s[0:1], 0xa8
	s_load_dword s9, s[0:1], 0xb0
	s_add_u32 s6, s34, 0x4200
	s_addc_u32 s7, s35, 0
	s_add_u32 s8, s34, 0x4400
	s_waitcnt lgkmcnt(0)
	s_mul_i32 s54, s13, s12
	s_mul_i32 s54, s54, s9
	s_addc_u32 s9, s35, 0
	s_add_u32 s12, s34, 0x4500
	s_addc_u32 s13, s35, 0
	s_add_u32 s14, s34, 0x4600
	s_addc_u32 s15, s35, 0
	s_add_u32 s16, s34, 0x4700
	s_addc_u32 s17, s35, 0
	s_add_u32 s18, s34, 0x4800
	s_addc_u32 s19, s35, 0
	s_add_u32 s20, s34, 0x4900
	s_addc_u32 s21, s35, 0
	s_add_u32 s22, s34, 0x4a00
	s_addc_u32 s23, s35, 0
	s_add_u32 s24, s34, 0x4b00
	s_addc_u32 s25, s35, 0
	s_add_u32 s26, s34, 0x4c00
	s_addc_u32 s27, s35, 0
	s_add_u32 s28, s34, 0x4d00
	s_addc_u32 s29, s35, 0
	s_add_u32 s30, s34, 0x4e00
	s_addc_u32 s31, s35, 0
	s_add_u32 s36, s34, 0x4f00
	s_addc_u32 s37, s35, 0
	s_add_u32 s38, s34, 0x5000
	s_addc_u32 s39, s35, 0
	s_add_u32 s40, s34, 0x5100
	s_addc_u32 s41, s35, 0
	s_add_u32 s42, s34, 0x5200
	s_addc_u32 s43, s35, 0
	s_add_u32 s44, s34, 0x5300
	s_addc_u32 s45, s35, 0
	s_mov_b32 s55, 1
	v_mov_b32_e32 v16, 0
	s_branch .LBB0_1173

.Lfb_poll_10:
	global_load_dword v2, v0, s[52:53] sc1
	s_waitcnt vmcnt(0)
	v_readfirstlane_b32 s99, v2
	s_cmpk_lt_u32 s99, 0x140
	s_cbranch_scc0 .Lfb_done_10
	s_sleep 1
	s_branch .Lfb_poll_10
.Lfb_done_10:
	s_branch .LBB0_1289
.Leinv_10:
	ds_read_b32 v2, v0
	s_add_i32 s6, 0, 0x20164
	v_mov_b32_e32 v0, s6
	ds_read_b32 v0, v0
	s_waitcnt lgkmcnt(1)
	v_cmp_ne_u32_e32 vcc, 0, v2
	s_cbranch_vccnz .LBB0_1253
	s_load_dwordx2 s[10:11], s[0:1], 0xa8
	s_load_dword s9, s[0:1], 0xb0
	s_add_u32 s6, s34, 0x4200
	s_addc_u32 s7, s35, 0
	s_add_u32 s8, s34, 0x4400
	s_waitcnt lgkmcnt(0)
	s_mul_i32 s50, s11, s10
	s_mul_i32 s50, s50, s9
	s_addc_u32 s9, s35, 0
	s_add_u32 s10, s34, 0x4500
	s_addc_u32 s11, s35, 0
	s_add_u32 s12, s34, 0x4600
	s_addc_u32 s13, s35, 0
	s_add_u32 s14, s34, 0x4700
	s_addc_u32 s15, s35, 0
	s_add_u32 s16, s34, 0x4800
	s_addc_u32 s17, s35, 0
	s_add_u32 s18, s34, 0x4900
	s_addc_u32 s19, s35, 0
	s_add_u32 s20, s34, 0x4a00
	s_addc_u32 s21, s35, 0
	s_add_u32 s22, s34, 0x4b00
	s_addc_u32 s23, s35, 0
	s_add_u32 s24, s34, 0x4c00
	s_addc_u32 s25, s35, 0
	s_add_u32 s26, s34, 0x4d00
	s_addc_u32 s27, s35, 0
	s_add_u32 s28, s34, 0x4e00
	s_addc_u32 s29, s35, 0
	s_add_u32 s30, s34, 0x4f00
	s_addc_u32 s31, s35, 0
	s_add_u32 s36, s34, 0x5000
	s_addc_u32 s37, s35, 0
	s_add_u32 s38, s34, 0x5100
	s_addc_u32 s39, s35, 0
	s_add_u32 s40, s34, 0x5200
	s_addc_u32 s41, s35, 0
	s_add_u32 s42, s34, 0x5300
	s_addc_u32 s43, s35, 0
	s_mov_b32 s51, 1
	v_mov_b32_e32 v16, 0
	s_branch .LBB0_1241
